# selection phase 3 (fine) rewritten by hand: batched LDS gathers, branch-free blocks, 4/8/16-block variants, early-exit bisection
# speedup vs baseline: 1.0116x; 1.0082x over previous
.LBB0_491:
	s_andn2_saveexec_b64 s[0:1], s[48:49]
	s_cbranch_execz .LBB0_497
	s_mov_b64 s[100:101], exec
	v_add_u32_e32 v5, v1, v3
	v_lshl_add_u32 v224, v172, 2, v188
	v_sub_u32_e32 v225, v172, v3
	v_readfirstlane_b32 s98, v5
	v_readfirstlane_b32 s85, v3
	v_readfirstlane_b32 s42, v4
	v_readfirstlane_b32 s36, v2
	v_readfirstlane_b32 s84, v0
	v_readfirstlane_b32 s99, v186
	v_lshl_add_u32 v225, v225, 2, v188
	v_add_u32_e32 v225, 0x800, v225
	s_add_i32 s43, s36, s84
	s_sub_i32 s43, 0x100, s43
	s_sub_i32 s84, 0x100, s84
	s_lshl_b32 s36, s36, 2
	s_add_i32 s36, s36, s99
	s_lshl_b32 s84, s84, 2
	s_add_i32 s84, s84, s99
	s_cmpk_gt_i32 s98, 0x200
	s_cbranch_scc1 .Lfine_v16
	s_cmpk_gt_i32 s98, 0x100
	s_cbranch_scc1 .Lfine_v8
	s_sub_i32 s99, s85, 0
	v_cmp_gt_i32_e32 vcc, s99, v172
	v_cndmask_b32_e32 v226, v225, v224, vcc
	ds_read_b32 v96, v226
	s_sub_i32 s99, s85, 64
	v_cmp_gt_i32_e32 vcc, s99, v172
	v_cndmask_b32_e32 v226, v225, v224, vcc
	ds_read_b32 v97, v226 offset:256
	s_sub_i32 s99, s85, 128
	v_cmp_gt_i32_e32 vcc, s99, v172
	v_cndmask_b32_e32 v226, v225, v224, vcc
	ds_read_b32 v98, v226 offset:512
	s_sub_i32 s99, s85, 192
	v_cmp_gt_i32_e32 vcc, s99, v172
	v_cndmask_b32_e32 v226, v225, v224, vcc
	ds_read_b32 v99, v226 offset:768
	s_waitcnt lgkmcnt(0)
	s_sub_i32 s99, s98, 0
	v_cmp_gt_i32_e32 vcc, s99, v172
	v_cndmask_b32_e32 v96, 0, v96, vcc
	v_lshl_add_u32 v226, v96, 2, v189
	ds_read_b32 v112, v226
	s_sub_i32 s99, s98, 64
	v_cmp_gt_i32_e32 vcc, s99, v172
	v_cndmask_b32_e32 v97, 0, v97, vcc
	v_lshl_add_u32 v226, v97, 2, v189
	ds_read_b32 v113, v226
	s_sub_i32 s99, s98, 128
	v_cmp_gt_i32_e32 vcc, s99, v172
	v_cndmask_b32_e32 v98, 0, v98, vcc
	v_lshl_add_u32 v226, v98, 2, v189
	ds_read_b32 v114, v226
	s_sub_i32 s99, s98, 192
	v_cmp_gt_i32_e32 vcc, s99, v172
	v_cndmask_b32_e32 v99, 0, v99, vcc
	v_lshl_add_u32 v226, v99, 2, v189
	ds_read_b32 v115, v226
	s_waitcnt lgkmcnt(0)
	s_sub_i32 s99, s98, 0
	v_cmp_gt_i32_e32 vcc, s99, v172
	v_cndmask_b32_e32 v112, 0, v112, vcc
	s_sub_i32 s99, s98, 64
	v_cmp_gt_i32_e32 vcc, s99, v172
	v_cndmask_b32_e32 v113, 0, v113, vcc
	s_sub_i32 s99, s98, 128
	v_cmp_gt_i32_e32 vcc, s99, v172
	v_cndmask_b32_e32 v114, 0, v114, vcc
	s_sub_i32 s99, s98, 192
	v_cmp_gt_i32_e32 vcc, s99, v172
	v_cndmask_b32_e32 v115, 0, v115, vcc
	s_mov_b32 s85, 20
.Lfine_bit_4:
	s_lshl_b32 s98, 1, s85
	s_or_b32 s98, s42, s98
	s_mov_b32 s37, 0
	v_cmp_le_u32_e64 s[46:47], s98, v112
	v_cmp_le_u32_e64 s[48:49], s98, v113
	v_cmp_le_u32_e64 s[58:59], s98, v114
	s_bcnt1_i32_b64 s99, s[46:47]
	s_add_i32 s37, s37, s99
	v_cmp_le_u32_e64 s[80:81], s98, v115
	s_bcnt1_i32_b64 s99, s[48:49]
	s_add_i32 s37, s37, s99
	s_bcnt1_i32_b64 s99, s[58:59]
	s_add_i32 s37, s37, s99
	s_bcnt1_i32_b64 s99, s[80:81]
	s_add_i32 s37, s37, s99
	s_cmp_ge_i32 s37, s43
	s_cselect_b32 s42, s98, s42
	s_cmp_eq_u32 s37, s43
	s_cbranch_scc1 .Lfine_sel_4
	s_add_i32 s85, s85, -1
	s_cmp_ge_i32 s85, 0
	s_cbranch_scc1 .Lfine_bit_4
.Lfine_sel_4:
	v_cmp_gt_u32_e64 s[46:47], v112, s42
	s_nop 1
	v_mbcnt_lo_u32_b32 v226, s46, 0
	v_mbcnt_hi_u32_b32 v226, s47, v226
	v_lshl_add_u32 v226, v226, 2, s36
	s_mov_b64 exec, s[46:47]
	ds_write_b32 v226, v96
	s_mov_b64 exec, s[100:101]
	s_bcnt1_i32_b64 s99, s[46:47]
	s_lshl_b32 s99, s99, 2
	s_add_i32 s36, s36, s99
	v_cmp_gt_u32_e64 s[48:49], v113, s42
	s_nop 1
	v_mbcnt_lo_u32_b32 v226, s48, 0
	v_mbcnt_hi_u32_b32 v226, s49, v226
	v_lshl_add_u32 v226, v226, 2, s36
	s_mov_b64 exec, s[48:49]
	ds_write_b32 v226, v97
	s_mov_b64 exec, s[100:101]
	s_bcnt1_i32_b64 s99, s[48:49]
	s_lshl_b32 s99, s99, 2
	s_add_i32 s36, s36, s99
	v_cmp_gt_u32_e64 s[46:47], v114, s42
	s_nop 1
	v_mbcnt_lo_u32_b32 v226, s46, 0
	v_mbcnt_hi_u32_b32 v226, s47, v226
	v_lshl_add_u32 v226, v226, 2, s36
	s_mov_b64 exec, s[46:47]
	ds_write_b32 v226, v98
	s_mov_b64 exec, s[100:101]
	s_bcnt1_i32_b64 s99, s[46:47]
	s_lshl_b32 s99, s99, 2
	s_add_i32 s36, s36, s99
	v_cmp_gt_u32_e64 s[48:49], v115, s42
	s_nop 1
	v_mbcnt_lo_u32_b32 v226, s48, 0
	v_mbcnt_hi_u32_b32 v226, s49, v226
	v_lshl_add_u32 v226, v226, 2, s36
	s_mov_b64 exec, s[48:49]
	ds_write_b32 v226, v99
	s_mov_b64 exec, s[100:101]
	s_bcnt1_i32_b64 s99, s[48:49]
	s_lshl_b32 s99, s99, 2
	s_add_i32 s36, s36, s99
	v_cmp_eq_u32_e64 s[46:47], v112, s42
	s_nop 1
	v_mbcnt_lo_u32_b32 v226, s46, 0
	v_mbcnt_hi_u32_b32 v226, s47, v226
	v_lshl_add_u32 v226, v226, 2, s36
	v_cmp_gt_i32_e64 s[58:59], s84, v226
	s_bcnt1_i32_b64 s99, s[46:47]
	s_lshl_b32 s99, s99, 2
	s_and_b64 exec, s[46:47], s[58:59]
	ds_write_b32 v226, v96
	s_mov_b64 exec, s[100:101]
	s_add_i32 s36, s36, s99
	v_cmp_eq_u32_e64 s[48:49], v113, s42
	s_nop 1
	v_mbcnt_lo_u32_b32 v226, s48, 0
	v_mbcnt_hi_u32_b32 v226, s49, v226
	v_lshl_add_u32 v226, v226, 2, s36
	v_cmp_gt_i32_e64 s[80:81], s84, v226
	s_bcnt1_i32_b64 s99, s[48:49]
	s_lshl_b32 s99, s99, 2
	s_and_b64 exec, s[48:49], s[80:81]
	ds_write_b32 v226, v97
	s_mov_b64 exec, s[100:101]
	s_add_i32 s36, s36, s99
	v_cmp_eq_u32_e64 s[46:47], v114, s42
	s_nop 1
	v_mbcnt_lo_u32_b32 v226, s46, 0
	v_mbcnt_hi_u32_b32 v226, s47, v226
	v_lshl_add_u32 v226, v226, 2, s36
	v_cmp_gt_i32_e64 s[58:59], s84, v226
	s_bcnt1_i32_b64 s99, s[46:47]
	s_lshl_b32 s99, s99, 2
	s_and_b64 exec, s[46:47], s[58:59]
	ds_write_b32 v226, v98
	s_mov_b64 exec, s[100:101]
	s_add_i32 s36, s36, s99
	v_cmp_eq_u32_e64 s[48:49], v115, s42
	s_nop 1
	v_mbcnt_lo_u32_b32 v226, s48, 0
	v_mbcnt_hi_u32_b32 v226, s49, v226
	v_lshl_add_u32 v226, v226, 2, s36
	v_cmp_gt_i32_e64 s[80:81], s84, v226
	s_bcnt1_i32_b64 s99, s[48:49]
	s_lshl_b32 s99, s99, 2
	s_and_b64 exec, s[48:49], s[80:81]
	ds_write_b32 v226, v99
	s_mov_b64 exec, s[100:101]
	s_add_i32 s36, s36, s99
	s_branch .Lfine_done
.Lfine_v8:
	s_sub_i32 s99, s85, 0
	v_cmp_gt_i32_e32 vcc, s99, v172
	v_cndmask_b32_e32 v226, v225, v224, vcc
	ds_read_b32 v96, v226
	s_sub_i32 s99, s85, 64
	v_cmp_gt_i32_e32 vcc, s99, v172
	v_cndmask_b32_e32 v226, v225, v224, vcc
	ds_read_b32 v97, v226 offset:256
	s_sub_i32 s99, s85, 128
	v_cmp_gt_i32_e32 vcc, s99, v172
	v_cndmask_b32_e32 v226, v225, v224, vcc
	ds_read_b32 v98, v226 offset:512
	s_sub_i32 s99, s85, 192
	v_cmp_gt_i32_e32 vcc, s99, v172
	v_cndmask_b32_e32 v226, v225, v224, vcc
	ds_read_b32 v99, v226 offset:768
	s_sub_i32 s99, s85, 256
	v_cmp_gt_i32_e32 vcc, s99, v172
	v_cndmask_b32_e32 v226, v225, v224, vcc
	ds_read_b32 v100, v226 offset:1024
	s_sub_i32 s99, s85, 320
	v_cmp_gt_i32_e32 vcc, s99, v172
	v_cndmask_b32_e32 v226, v225, v224, vcc
	ds_read_b32 v101, v226 offset:1280
	s_sub_i32 s99, s85, 384
	v_cmp_gt_i32_e32 vcc, s99, v172
	v_cndmask_b32_e32 v226, v225, v224, vcc
	ds_read_b32 v102, v226 offset:1536
	s_sub_i32 s99, s85, 448
	v_cmp_gt_i32_e32 vcc, s99, v172
	v_cndmask_b32_e32 v226, v225, v224, vcc
	ds_read_b32 v103, v226 offset:1792
	s_waitcnt lgkmcnt(0)
	s_sub_i32 s99, s98, 0
	v_cmp_gt_i32_e32 vcc, s99, v172
	v_cndmask_b32_e32 v96, 0, v96, vcc
	v_lshl_add_u32 v226, v96, 2, v189
	ds_read_b32 v112, v226
	s_sub_i32 s99, s98, 64
	v_cmp_gt_i32_e32 vcc, s99, v172
	v_cndmask_b32_e32 v97, 0, v97, vcc
	v_lshl_add_u32 v226, v97, 2, v189
	ds_read_b32 v113, v226
	s_sub_i32 s99, s98, 128
	v_cmp_gt_i32_e32 vcc, s99, v172
	v_cndmask_b32_e32 v98, 0, v98, vcc
	v_lshl_add_u32 v226, v98, 2, v189
	ds_read_b32 v114, v226
	s_sub_i32 s99, s98, 192
	v_cmp_gt_i32_e32 vcc, s99, v172
	v_cndmask_b32_e32 v99, 0, v99, vcc
	v_lshl_add_u32 v226, v99, 2, v189
	ds_read_b32 v115, v226
	s_sub_i32 s99, s98, 256
	v_cmp_gt_i32_e32 vcc, s99, v172
	v_cndmask_b32_e32 v100, 0, v100, vcc
	v_lshl_add_u32 v226, v100, 2, v189
	ds_read_b32 v116, v226
	s_sub_i32 s99, s98, 320
	v_cmp_gt_i32_e32 vcc, s99, v172
	v_cndmask_b32_e32 v101, 0, v101, vcc
	v_lshl_add_u32 v226, v101, 2, v189
	ds_read_b32 v117, v226
	s_sub_i32 s99, s98, 384
	v_cmp_gt_i32_e32 vcc, s99, v172
	v_cndmask_b32_e32 v102, 0, v102, vcc
	v_lshl_add_u32 v226, v102, 2, v189
	ds_read_b32 v118, v226
	s_sub_i32 s99, s98, 448
	v_cmp_gt_i32_e32 vcc, s99, v172
	v_cndmask_b32_e32 v103, 0, v103, vcc
	v_lshl_add_u32 v226, v103, 2, v189
	ds_read_b32 v119, v226
	s_waitcnt lgkmcnt(0)
	s_sub_i32 s99, s98, 0
	v_cmp_gt_i32_e32 vcc, s99, v172
	v_cndmask_b32_e32 v112, 0, v112, vcc
	s_sub_i32 s99, s98, 64
	v_cmp_gt_i32_e32 vcc, s99, v172
	v_cndmask_b32_e32 v113, 0, v113, vcc
	s_sub_i32 s99, s98, 128
	v_cmp_gt_i32_e32 vcc, s99, v172
	v_cndmask_b32_e32 v114, 0, v114, vcc
	s_sub_i32 s99, s98, 192
	v_cmp_gt_i32_e32 vcc, s99, v172
	v_cndmask_b32_e32 v115, 0, v115, vcc
	s_sub_i32 s99, s98, 256
	v_cmp_gt_i32_e32 vcc, s99, v172
	v_cndmask_b32_e32 v116, 0, v116, vcc
	s_sub_i32 s99, s98, 320
	v_cmp_gt_i32_e32 vcc, s99, v172
	v_cndmask_b32_e32 v117, 0, v117, vcc
	s_sub_i32 s99, s98, 384
	v_cmp_gt_i32_e32 vcc, s99, v172
	v_cndmask_b32_e32 v118, 0, v118, vcc
	s_sub_i32 s99, s98, 448
	v_cmp_gt_i32_e32 vcc, s99, v172
	v_cndmask_b32_e32 v119, 0, v119, vcc
	s_mov_b32 s85, 20
.Lfine_bit_8:
	s_lshl_b32 s98, 1, s85
	s_or_b32 s98, s42, s98
	s_mov_b32 s37, 0
	v_cmp_le_u32_e64 s[46:47], s98, v112
	v_cmp_le_u32_e64 s[48:49], s98, v113
	v_cmp_le_u32_e64 s[58:59], s98, v114
	s_bcnt1_i32_b64 s99, s[46:47]
	s_add_i32 s37, s37, s99
	v_cmp_le_u32_e64 s[80:81], s98, v115
	s_bcnt1_i32_b64 s99, s[48:49]
	s_add_i32 s37, s37, s99
	v_cmp_le_u32_e64 s[46:47], s98, v116
	s_bcnt1_i32_b64 s99, s[58:59]
	s_add_i32 s37, s37, s99
	v_cmp_le_u32_e64 s[48:49], s98, v117
	s_bcnt1_i32_b64 s99, s[80:81]
	s_add_i32 s37, s37, s99
	v_cmp_le_u32_e64 s[58:59], s98, v118
	s_bcnt1_i32_b64 s99, s[46:47]
	s_add_i32 s37, s37, s99
	v_cmp_le_u32_e64 s[80:81], s98, v119
	s_bcnt1_i32_b64 s99, s[48:49]
	s_add_i32 s37, s37, s99
	s_bcnt1_i32_b64 s99, s[58:59]
	s_add_i32 s37, s37, s99
	s_bcnt1_i32_b64 s99, s[80:81]
	s_add_i32 s37, s37, s99
	s_cmp_ge_i32 s37, s43
	s_cselect_b32 s42, s98, s42
	s_cmp_eq_u32 s37, s43
	s_cbranch_scc1 .Lfine_sel_8
	s_add_i32 s85, s85, -1
	s_cmp_ge_i32 s85, 0
	s_cbranch_scc1 .Lfine_bit_8
.Lfine_sel_8:
	v_cmp_gt_u32_e64 s[46:47], v112, s42
	s_nop 1
	v_mbcnt_lo_u32_b32 v226, s46, 0
	v_mbcnt_hi_u32_b32 v226, s47, v226
	v_lshl_add_u32 v226, v226, 2, s36
	s_mov_b64 exec, s[46:47]
	ds_write_b32 v226, v96
	s_mov_b64 exec, s[100:101]
	s_bcnt1_i32_b64 s99, s[46:47]
	s_lshl_b32 s99, s99, 2
	s_add_i32 s36, s36, s99
	v_cmp_gt_u32_e64 s[48:49], v113, s42
	s_nop 1
	v_mbcnt_lo_u32_b32 v226, s48, 0
	v_mbcnt_hi_u32_b32 v226, s49, v226
	v_lshl_add_u32 v226, v226, 2, s36
	s_mov_b64 exec, s[48:49]
	ds_write_b32 v226, v97
	s_mov_b64 exec, s[100:101]
	s_bcnt1_i32_b64 s99, s[48:49]
	s_lshl_b32 s99, s99, 2
	s_add_i32 s36, s36, s99
	v_cmp_gt_u32_e64 s[46:47], v114, s42
	s_nop 1
	v_mbcnt_lo_u32_b32 v226, s46, 0
	v_mbcnt_hi_u32_b32 v226, s47, v226
	v_lshl_add_u32 v226, v226, 2, s36
	s_mov_b64 exec, s[46:47]
	ds_write_b32 v226, v98
	s_mov_b64 exec, s[100:101]
	s_bcnt1_i32_b64 s99, s[46:47]
	s_lshl_b32 s99, s99, 2
	s_add_i32 s36, s36, s99
	v_cmp_gt_u32_e64 s[48:49], v115, s42
	s_nop 1
	v_mbcnt_lo_u32_b32 v226, s48, 0
	v_mbcnt_hi_u32_b32 v226, s49, v226
	v_lshl_add_u32 v226, v226, 2, s36
	s_mov_b64 exec, s[48:49]
	ds_write_b32 v226, v99
	s_mov_b64 exec, s[100:101]
	s_bcnt1_i32_b64 s99, s[48:49]
	s_lshl_b32 s99, s99, 2
	s_add_i32 s36, s36, s99
	v_cmp_gt_u32_e64 s[46:47], v116, s42
	s_nop 1
	v_mbcnt_lo_u32_b32 v226, s46, 0
	v_mbcnt_hi_u32_b32 v226, s47, v226
	v_lshl_add_u32 v226, v226, 2, s36
	s_mov_b64 exec, s[46:47]
	ds_write_b32 v226, v100
	s_mov_b64 exec, s[100:101]
	s_bcnt1_i32_b64 s99, s[46:47]
	s_lshl_b32 s99, s99, 2
	s_add_i32 s36, s36, s99
	v_cmp_gt_u32_e64 s[48:49], v117, s42
	s_nop 1
	v_mbcnt_lo_u32_b32 v226, s48, 0
	v_mbcnt_hi_u32_b32 v226, s49, v226
	v_lshl_add_u32 v226, v226, 2, s36
	s_mov_b64 exec, s[48:49]
	ds_write_b32 v226, v101
	s_mov_b64 exec, s[100:101]
	s_bcnt1_i32_b64 s99, s[48:49]
	s_lshl_b32 s99, s99, 2
	s_add_i32 s36, s36, s99
	v_cmp_gt_u32_e64 s[46:47], v118, s42
	s_nop 1
	v_mbcnt_lo_u32_b32 v226, s46, 0
	v_mbcnt_hi_u32_b32 v226, s47, v226
	v_lshl_add_u32 v226, v226, 2, s36
	s_mov_b64 exec, s[46:47]
	ds_write_b32 v226, v102
	s_mov_b64 exec, s[100:101]
	s_bcnt1_i32_b64 s99, s[46:47]
	s_lshl_b32 s99, s99, 2
	s_add_i32 s36, s36, s99
	v_cmp_gt_u32_e64 s[48:49], v119, s42
	s_nop 1
	v_mbcnt_lo_u32_b32 v226, s48, 0
	v_mbcnt_hi_u32_b32 v226, s49, v226
	v_lshl_add_u32 v226, v226, 2, s36
	s_mov_b64 exec, s[48:49]
	ds_write_b32 v226, v103
	s_mov_b64 exec, s[100:101]
	s_bcnt1_i32_b64 s99, s[48:49]
	s_lshl_b32 s99, s99, 2
	s_add_i32 s36, s36, s99
	v_cmp_eq_u32_e64 s[46:47], v112, s42
	s_nop 1
	v_mbcnt_lo_u32_b32 v226, s46, 0
	v_mbcnt_hi_u32_b32 v226, s47, v226
	v_lshl_add_u32 v226, v226, 2, s36
	v_cmp_gt_i32_e64 s[58:59], s84, v226
	s_bcnt1_i32_b64 s99, s[46:47]
	s_lshl_b32 s99, s99, 2
	s_and_b64 exec, s[46:47], s[58:59]
	ds_write_b32 v226, v96
	s_mov_b64 exec, s[100:101]
	s_add_i32 s36, s36, s99
	v_cmp_eq_u32_e64 s[48:49], v113, s42
	s_nop 1
	v_mbcnt_lo_u32_b32 v226, s48, 0
	v_mbcnt_hi_u32_b32 v226, s49, v226
	v_lshl_add_u32 v226, v226, 2, s36
	v_cmp_gt_i32_e64 s[80:81], s84, v226
	s_bcnt1_i32_b64 s99, s[48:49]
	s_lshl_b32 s99, s99, 2
	s_and_b64 exec, s[48:49], s[80:81]
	ds_write_b32 v226, v97
	s_mov_b64 exec, s[100:101]
	s_add_i32 s36, s36, s99
	v_cmp_eq_u32_e64 s[46:47], v114, s42
	s_nop 1
	v_mbcnt_lo_u32_b32 v226, s46, 0
	v_mbcnt_hi_u32_b32 v226, s47, v226
	v_lshl_add_u32 v226, v226, 2, s36
	v_cmp_gt_i32_e64 s[58:59], s84, v226
	s_bcnt1_i32_b64 s99, s[46:47]
	s_lshl_b32 s99, s99, 2
	s_and_b64 exec, s[46:47], s[58:59]
	ds_write_b32 v226, v98
	s_mov_b64 exec, s[100:101]
	s_add_i32 s36, s36, s99
	v_cmp_eq_u32_e64 s[48:49], v115, s42
	s_nop 1
	v_mbcnt_lo_u32_b32 v226, s48, 0
	v_mbcnt_hi_u32_b32 v226, s49, v226
	v_lshl_add_u32 v226, v226, 2, s36
	v_cmp_gt_i32_e64 s[80:81], s84, v226
	s_bcnt1_i32_b64 s99, s[48:49]
	s_lshl_b32 s99, s99, 2
	s_and_b64 exec, s[48:49], s[80:81]
	ds_write_b32 v226, v99
	s_mov_b64 exec, s[100:101]
	s_add_i32 s36, s36, s99
	v_cmp_eq_u32_e64 s[46:47], v116, s42
	s_nop 1
	v_mbcnt_lo_u32_b32 v226, s46, 0
	v_mbcnt_hi_u32_b32 v226, s47, v226
	v_lshl_add_u32 v226, v226, 2, s36
	v_cmp_gt_i32_e64 s[58:59], s84, v226
	s_bcnt1_i32_b64 s99, s[46:47]
	s_lshl_b32 s99, s99, 2
	s_and_b64 exec, s[46:47], s[58:59]
	ds_write_b32 v226, v100
	s_mov_b64 exec, s[100:101]
	s_add_i32 s36, s36, s99
	v_cmp_eq_u32_e64 s[48:49], v117, s42
	s_nop 1
	v_mbcnt_lo_u32_b32 v226, s48, 0
	v_mbcnt_hi_u32_b32 v226, s49, v226
	v_lshl_add_u32 v226, v226, 2, s36
	v_cmp_gt_i32_e64 s[80:81], s84, v226
	s_bcnt1_i32_b64 s99, s[48:49]
	s_lshl_b32 s99, s99, 2
	s_and_b64 exec, s[48:49], s[80:81]
	ds_write_b32 v226, v101
	s_mov_b64 exec, s[100:101]
	s_add_i32 s36, s36, s99
	v_cmp_eq_u32_e64 s[46:47], v118, s42
	s_nop 1
	v_mbcnt_lo_u32_b32 v226, s46, 0
	v_mbcnt_hi_u32_b32 v226, s47, v226
	v_lshl_add_u32 v226, v226, 2, s36
	v_cmp_gt_i32_e64 s[58:59], s84, v226
	s_bcnt1_i32_b64 s99, s[46:47]
	s_lshl_b32 s99, s99, 2
	s_and_b64 exec, s[46:47], s[58:59]
	ds_write_b32 v226, v102
	s_mov_b64 exec, s[100:101]
	s_add_i32 s36, s36, s99
	v_cmp_eq_u32_e64 s[48:49], v119, s42
	s_nop 1
	v_mbcnt_lo_u32_b32 v226, s48, 0
	v_mbcnt_hi_u32_b32 v226, s49, v226
	v_lshl_add_u32 v226, v226, 2, s36
	v_cmp_gt_i32_e64 s[80:81], s84, v226
	s_bcnt1_i32_b64 s99, s[48:49]
	s_lshl_b32 s99, s99, 2
	s_and_b64 exec, s[48:49], s[80:81]
	ds_write_b32 v226, v103
	s_mov_b64 exec, s[100:101]
	s_add_i32 s36, s36, s99
	s_branch .Lfine_done
.Lfine_v16:
	s_sub_i32 s99, s85, 0
	v_cmp_gt_i32_e32 vcc, s99, v172
	v_cndmask_b32_e32 v226, v225, v224, vcc
	ds_read_b32 v96, v226
	s_sub_i32 s99, s85, 64
	v_cmp_gt_i32_e32 vcc, s99, v172
	v_cndmask_b32_e32 v226, v225, v224, vcc
	ds_read_b32 v97, v226 offset:256
	s_sub_i32 s99, s85, 128
	v_cmp_gt_i32_e32 vcc, s99, v172
	v_cndmask_b32_e32 v226, v225, v224, vcc
	ds_read_b32 v98, v226 offset:512
	s_sub_i32 s99, s85, 192
	v_cmp_gt_i32_e32 vcc, s99, v172
	v_cndmask_b32_e32 v226, v225, v224, vcc
	ds_read_b32 v99, v226 offset:768
	s_sub_i32 s99, s85, 256
	v_cmp_gt_i32_e32 vcc, s99, v172
	v_cndmask_b32_e32 v226, v225, v224, vcc
	ds_read_b32 v100, v226 offset:1024
	s_sub_i32 s99, s85, 320
	v_cmp_gt_i32_e32 vcc, s99, v172
	v_cndmask_b32_e32 v226, v225, v224, vcc
	ds_read_b32 v101, v226 offset:1280
	s_sub_i32 s99, s85, 384
	v_cmp_gt_i32_e32 vcc, s99, v172
	v_cndmask_b32_e32 v226, v225, v224, vcc
	ds_read_b32 v102, v226 offset:1536
	s_sub_i32 s99, s85, 448
	v_cmp_gt_i32_e32 vcc, s99, v172
	v_cndmask_b32_e32 v226, v225, v224, vcc
	ds_read_b32 v103, v226 offset:1792
	s_sub_i32 s99, s85, 512
	v_cmp_gt_i32_e32 vcc, s99, v172
	v_cndmask_b32_e32 v226, v225, v224, vcc
	ds_read_b32 v104, v226 offset:2048
	s_sub_i32 s99, s85, 576
	v_cmp_gt_i32_e32 vcc, s99, v172
	v_cndmask_b32_e32 v226, v225, v224, vcc
	ds_read_b32 v105, v226 offset:2304
	s_sub_i32 s99, s85, 640
	v_cmp_gt_i32_e32 vcc, s99, v172
	v_cndmask_b32_e32 v226, v225, v224, vcc
	ds_read_b32 v106, v226 offset:2560
	s_sub_i32 s99, s85, 704
	v_cmp_gt_i32_e32 vcc, s99, v172
	v_cndmask_b32_e32 v226, v225, v224, vcc
	ds_read_b32 v107, v226 offset:2816
	s_sub_i32 s99, s85, 768
	v_cmp_gt_i32_e32 vcc, s99, v172
	v_cndmask_b32_e32 v226, v225, v224, vcc
	ds_read_b32 v108, v226 offset:3072
	s_sub_i32 s99, s85, 832
	v_cmp_gt_i32_e32 vcc, s99, v172
	v_cndmask_b32_e32 v226, v225, v224, vcc
	ds_read_b32 v109, v226 offset:3328
	s_sub_i32 s99, s85, 896
	v_cmp_gt_i32_e32 vcc, s99, v172
	v_cndmask_b32_e32 v226, v225, v224, vcc
	ds_read_b32 v110, v226 offset:3584
	s_sub_i32 s99, s85, 960
	v_cmp_gt_i32_e32 vcc, s99, v172
	v_cndmask_b32_e32 v226, v225, v224, vcc
	ds_read_b32 v111, v226 offset:3840
	s_waitcnt lgkmcnt(0)
	s_sub_i32 s99, s98, 0
	v_cmp_gt_i32_e32 vcc, s99, v172
	v_cndmask_b32_e32 v96, 0, v96, vcc
	v_lshl_add_u32 v226, v96, 2, v189
	ds_read_b32 v112, v226
	s_sub_i32 s99, s98, 64
	v_cmp_gt_i32_e32 vcc, s99, v172
	v_cndmask_b32_e32 v97, 0, v97, vcc
	v_lshl_add_u32 v226, v97, 2, v189
	ds_read_b32 v113, v226
	s_sub_i32 s99, s98, 128
	v_cmp_gt_i32_e32 vcc, s99, v172
	v_cndmask_b32_e32 v98, 0, v98, vcc
	v_lshl_add_u32 v226, v98, 2, v189
	ds_read_b32 v114, v226
	s_sub_i32 s99, s98, 192
	v_cmp_gt_i32_e32 vcc, s99, v172
	v_cndmask_b32_e32 v99, 0, v99, vcc
	v_lshl_add_u32 v226, v99, 2, v189
	ds_read_b32 v115, v226
	s_sub_i32 s99, s98, 256
	v_cmp_gt_i32_e32 vcc, s99, v172
	v_cndmask_b32_e32 v100, 0, v100, vcc
	v_lshl_add_u32 v226, v100, 2, v189
	ds_read_b32 v116, v226
	s_sub_i32 s99, s98, 320
	v_cmp_gt_i32_e32 vcc, s99, v172
	v_cndmask_b32_e32 v101, 0, v101, vcc
	v_lshl_add_u32 v226, v101, 2, v189
	ds_read_b32 v117, v226
	s_sub_i32 s99, s98, 384
	v_cmp_gt_i32_e32 vcc, s99, v172
	v_cndmask_b32_e32 v102, 0, v102, vcc
	v_lshl_add_u32 v226, v102, 2, v189
	ds_read_b32 v118, v226
	s_sub_i32 s99, s98, 448
	v_cmp_gt_i32_e32 vcc, s99, v172
	v_cndmask_b32_e32 v103, 0, v103, vcc
	v_lshl_add_u32 v226, v103, 2, v189
	ds_read_b32 v119, v226
	s_sub_i32 s99, s98, 512
	v_cmp_gt_i32_e32 vcc, s99, v172
	v_cndmask_b32_e32 v104, 0, v104, vcc
	v_lshl_add_u32 v226, v104, 2, v189
	ds_read_b32 v120, v226
	s_sub_i32 s99, s98, 576
	v_cmp_gt_i32_e32 vcc, s99, v172
	v_cndmask_b32_e32 v105, 0, v105, vcc
	v_lshl_add_u32 v226, v105, 2, v189
	ds_read_b32 v121, v226
	s_sub_i32 s99, s98, 640
	v_cmp_gt_i32_e32 vcc, s99, v172
	v_cndmask_b32_e32 v106, 0, v106, vcc
	v_lshl_add_u32 v226, v106, 2, v189
	ds_read_b32 v122, v226
	s_sub_i32 s99, s98, 704
	v_cmp_gt_i32_e32 vcc, s99, v172
	v_cndmask_b32_e32 v107, 0, v107, vcc
	v_lshl_add_u32 v226, v107, 2, v189
	ds_read_b32 v123, v226
	s_sub_i32 s99, s98, 768
	v_cmp_gt_i32_e32 vcc, s99, v172
	v_cndmask_b32_e32 v108, 0, v108, vcc
	v_lshl_add_u32 v226, v108, 2, v189
	ds_read_b32 v124, v226
	s_sub_i32 s99, s98, 832
	v_cmp_gt_i32_e32 vcc, s99, v172
	v_cndmask_b32_e32 v109, 0, v109, vcc
	v_lshl_add_u32 v226, v109, 2, v189
	ds_read_b32 v125, v226
	s_sub_i32 s99, s98, 896
	v_cmp_gt_i32_e32 vcc, s99, v172
	v_cndmask_b32_e32 v110, 0, v110, vcc
	v_lshl_add_u32 v226, v110, 2, v189
	ds_read_b32 v126, v226
	s_sub_i32 s99, s98, 960
	v_cmp_gt_i32_e32 vcc, s99, v172
	v_cndmask_b32_e32 v111, 0, v111, vcc
	v_lshl_add_u32 v226, v111, 2, v189
	ds_read_b32 v127, v226
	s_waitcnt lgkmcnt(0)
	s_sub_i32 s99, s98, 0
	v_cmp_gt_i32_e32 vcc, s99, v172
	v_cndmask_b32_e32 v112, 0, v112, vcc
	s_sub_i32 s99, s98, 64
	v_cmp_gt_i32_e32 vcc, s99, v172
	v_cndmask_b32_e32 v113, 0, v113, vcc
	s_sub_i32 s99, s98, 128
	v_cmp_gt_i32_e32 vcc, s99, v172
	v_cndmask_b32_e32 v114, 0, v114, vcc
	s_sub_i32 s99, s98, 192
	v_cmp_gt_i32_e32 vcc, s99, v172
	v_cndmask_b32_e32 v115, 0, v115, vcc
	s_sub_i32 s99, s98, 256
	v_cmp_gt_i32_e32 vcc, s99, v172
	v_cndmask_b32_e32 v116, 0, v116, vcc
	s_sub_i32 s99, s98, 320
	v_cmp_gt_i32_e32 vcc, s99, v172
	v_cndmask_b32_e32 v117, 0, v117, vcc
	s_sub_i32 s99, s98, 384
	v_cmp_gt_i32_e32 vcc, s99, v172
	v_cndmask_b32_e32 v118, 0, v118, vcc
	s_sub_i32 s99, s98, 448
	v_cmp_gt_i32_e32 vcc, s99, v172
	v_cndmask_b32_e32 v119, 0, v119, vcc
	s_sub_i32 s99, s98, 512
	v_cmp_gt_i32_e32 vcc, s99, v172
	v_cndmask_b32_e32 v120, 0, v120, vcc
	s_sub_i32 s99, s98, 576
	v_cmp_gt_i32_e32 vcc, s99, v172
	v_cndmask_b32_e32 v121, 0, v121, vcc
	s_sub_i32 s99, s98, 640
	v_cmp_gt_i32_e32 vcc, s99, v172
	v_cndmask_b32_e32 v122, 0, v122, vcc
	s_sub_i32 s99, s98, 704
	v_cmp_gt_i32_e32 vcc, s99, v172
	v_cndmask_b32_e32 v123, 0, v123, vcc
	s_sub_i32 s99, s98, 768
	v_cmp_gt_i32_e32 vcc, s99, v172
	v_cndmask_b32_e32 v124, 0, v124, vcc
	s_sub_i32 s99, s98, 832
	v_cmp_gt_i32_e32 vcc, s99, v172
	v_cndmask_b32_e32 v125, 0, v125, vcc
	s_sub_i32 s99, s98, 896
	v_cmp_gt_i32_e32 vcc, s99, v172
	v_cndmask_b32_e32 v126, 0, v126, vcc
	s_sub_i32 s99, s98, 960
	v_cmp_gt_i32_e32 vcc, s99, v172
	v_cndmask_b32_e32 v127, 0, v127, vcc
	s_mov_b32 s85, 20
.Lfine_bit_16:
	s_lshl_b32 s98, 1, s85
	s_or_b32 s98, s42, s98
	s_mov_b32 s37, 0
	v_cmp_le_u32_e64 s[46:47], s98, v112
	v_cmp_le_u32_e64 s[48:49], s98, v113
	v_cmp_le_u32_e64 s[58:59], s98, v114
	s_bcnt1_i32_b64 s99, s[46:47]
	s_add_i32 s37, s37, s99
	v_cmp_le_u32_e64 s[80:81], s98, v115
	s_bcnt1_i32_b64 s99, s[48:49]
	s_add_i32 s37, s37, s99
	v_cmp_le_u32_e64 s[46:47], s98, v116
	s_bcnt1_i32_b64 s99, s[58:59]
	s_add_i32 s37, s37, s99
	v_cmp_le_u32_e64 s[48:49], s98, v117
	s_bcnt1_i32_b64 s99, s[80:81]
	s_add_i32 s37, s37, s99
	v_cmp_le_u32_e64 s[58:59], s98, v118
	s_bcnt1_i32_b64 s99, s[46:47]
	s_add_i32 s37, s37, s99
	v_cmp_le_u32_e64 s[80:81], s98, v119
	s_bcnt1_i32_b64 s99, s[48:49]
	s_add_i32 s37, s37, s99
	v_cmp_le_u32_e64 s[46:47], s98, v120
	s_bcnt1_i32_b64 s99, s[58:59]
	s_add_i32 s37, s37, s99
	v_cmp_le_u32_e64 s[48:49], s98, v121
	s_bcnt1_i32_b64 s99, s[80:81]
	s_add_i32 s37, s37, s99
	v_cmp_le_u32_e64 s[58:59], s98, v122
	s_bcnt1_i32_b64 s99, s[46:47]
	s_add_i32 s37, s37, s99
	v_cmp_le_u32_e64 s[80:81], s98, v123
	s_bcnt1_i32_b64 s99, s[48:49]
	s_add_i32 s37, s37, s99
	v_cmp_le_u32_e64 s[46:47], s98, v124
	s_bcnt1_i32_b64 s99, s[58:59]
	s_add_i32 s37, s37, s99
	v_cmp_le_u32_e64 s[48:49], s98, v125
	s_bcnt1_i32_b64 s99, s[80:81]
	s_add_i32 s37, s37, s99
	v_cmp_le_u32_e64 s[58:59], s98, v126
	s_bcnt1_i32_b64 s99, s[46:47]
	s_add_i32 s37, s37, s99
	v_cmp_le_u32_e64 s[80:81], s98, v127
	s_bcnt1_i32_b64 s99, s[48:49]
	s_add_i32 s37, s37, s99
	s_bcnt1_i32_b64 s99, s[58:59]
	s_add_i32 s37, s37, s99
	s_bcnt1_i32_b64 s99, s[80:81]
	s_add_i32 s37, s37, s99
	s_cmp_ge_i32 s37, s43
	s_cselect_b32 s42, s98, s42
	s_cmp_eq_u32 s37, s43
	s_cbranch_scc1 .Lfine_sel_16
	s_add_i32 s85, s85, -1
	s_cmp_ge_i32 s85, 0
	s_cbranch_scc1 .Lfine_bit_16
.Lfine_sel_16:
	v_cmp_gt_u32_e64 s[46:47], v112, s42
	s_nop 1
	v_mbcnt_lo_u32_b32 v226, s46, 0
	v_mbcnt_hi_u32_b32 v226, s47, v226
	v_lshl_add_u32 v226, v226, 2, s36
	s_mov_b64 exec, s[46:47]
	ds_write_b32 v226, v96
	s_mov_b64 exec, s[100:101]
	s_bcnt1_i32_b64 s99, s[46:47]
	s_lshl_b32 s99, s99, 2
	s_add_i32 s36, s36, s99
	v_cmp_gt_u32_e64 s[48:49], v113, s42
	s_nop 1
	v_mbcnt_lo_u32_b32 v226, s48, 0
	v_mbcnt_hi_u32_b32 v226, s49, v226
	v_lshl_add_u32 v226, v226, 2, s36
	s_mov_b64 exec, s[48:49]
	ds_write_b32 v226, v97
	s_mov_b64 exec, s[100:101]
	s_bcnt1_i32_b64 s99, s[48:49]
	s_lshl_b32 s99, s99, 2
	s_add_i32 s36, s36, s99
	v_cmp_gt_u32_e64 s[46:47], v114, s42
	s_nop 1
	v_mbcnt_lo_u32_b32 v226, s46, 0
	v_mbcnt_hi_u32_b32 v226, s47, v226
	v_lshl_add_u32 v226, v226, 2, s36
	s_mov_b64 exec, s[46:47]
	ds_write_b32 v226, v98
	s_mov_b64 exec, s[100:101]
	s_bcnt1_i32_b64 s99, s[46:47]
	s_lshl_b32 s99, s99, 2
	s_add_i32 s36, s36, s99
	v_cmp_gt_u32_e64 s[48:49], v115, s42
	s_nop 1
	v_mbcnt_lo_u32_b32 v226, s48, 0
	v_mbcnt_hi_u32_b32 v226, s49, v226
	v_lshl_add_u32 v226, v226, 2, s36
	s_mov_b64 exec, s[48:49]
	ds_write_b32 v226, v99
	s_mov_b64 exec, s[100:101]
	s_bcnt1_i32_b64 s99, s[48:49]
	s_lshl_b32 s99, s99, 2
	s_add_i32 s36, s36, s99
	v_cmp_gt_u32_e64 s[46:47], v116, s42
	s_nop 1
	v_mbcnt_lo_u32_b32 v226, s46, 0
	v_mbcnt_hi_u32_b32 v226, s47, v226
	v_lshl_add_u32 v226, v226, 2, s36
	s_mov_b64 exec, s[46:47]
	ds_write_b32 v226, v100
	s_mov_b64 exec, s[100:101]
	s_bcnt1_i32_b64 s99, s[46:47]
	s_lshl_b32 s99, s99, 2
	s_add_i32 s36, s36, s99
	v_cmp_gt_u32_e64 s[48:49], v117, s42
	s_nop 1
	v_mbcnt_lo_u32_b32 v226, s48, 0
	v_mbcnt_hi_u32_b32 v226, s49, v226
	v_lshl_add_u32 v226, v226, 2, s36
	s_mov_b64 exec, s[48:49]
	ds_write_b32 v226, v101
	s_mov_b64 exec, s[100:101]
	s_bcnt1_i32_b64 s99, s[48:49]
	s_lshl_b32 s99, s99, 2
	s_add_i32 s36, s36, s99
	v_cmp_gt_u32_e64 s[46:47], v118, s42
	s_nop 1
	v_mbcnt_lo_u32_b32 v226, s46, 0
	v_mbcnt_hi_u32_b32 v226, s47, v226
	v_lshl_add_u32 v226, v226, 2, s36
	s_mov_b64 exec, s[46:47]
	ds_write_b32 v226, v102
	s_mov_b64 exec, s[100:101]
	s_bcnt1_i32_b64 s99, s[46:47]
	s_lshl_b32 s99, s99, 2
	s_add_i32 s36, s36, s99
	v_cmp_gt_u32_e64 s[48:49], v119, s42
	s_nop 1
	v_mbcnt_lo_u32_b32 v226, s48, 0
	v_mbcnt_hi_u32_b32 v226, s49, v226
	v_lshl_add_u32 v226, v226, 2, s36
	s_mov_b64 exec, s[48:49]
	ds_write_b32 v226, v103
	s_mov_b64 exec, s[100:101]
	s_bcnt1_i32_b64 s99, s[48:49]
	s_lshl_b32 s99, s99, 2
	s_add_i32 s36, s36, s99
	v_cmp_gt_u32_e64 s[46:47], v120, s42
	s_nop 1
	v_mbcnt_lo_u32_b32 v226, s46, 0
	v_mbcnt_hi_u32_b32 v226, s47, v226
	v_lshl_add_u32 v226, v226, 2, s36
	s_mov_b64 exec, s[46:47]
	ds_write_b32 v226, v104
	s_mov_b64 exec, s[100:101]
	s_bcnt1_i32_b64 s99, s[46:47]
	s_lshl_b32 s99, s99, 2
	s_add_i32 s36, s36, s99
	v_cmp_gt_u32_e64 s[48:49], v121, s42
	s_nop 1
	v_mbcnt_lo_u32_b32 v226, s48, 0
	v_mbcnt_hi_u32_b32 v226, s49, v226
	v_lshl_add_u32 v226, v226, 2, s36
	s_mov_b64 exec, s[48:49]
	ds_write_b32 v226, v105
	s_mov_b64 exec, s[100:101]
	s_bcnt1_i32_b64 s99, s[48:49]
	s_lshl_b32 s99, s99, 2
	s_add_i32 s36, s36, s99
	v_cmp_gt_u32_e64 s[46:47], v122, s42
	s_nop 1
	v_mbcnt_lo_u32_b32 v226, s46, 0
	v_mbcnt_hi_u32_b32 v226, s47, v226
	v_lshl_add_u32 v226, v226, 2, s36
	s_mov_b64 exec, s[46:47]
	ds_write_b32 v226, v106
	s_mov_b64 exec, s[100:101]
	s_bcnt1_i32_b64 s99, s[46:47]
	s_lshl_b32 s99, s99, 2
	s_add_i32 s36, s36, s99
	v_cmp_gt_u32_e64 s[48:49], v123, s42
	s_nop 1
	v_mbcnt_lo_u32_b32 v226, s48, 0
	v_mbcnt_hi_u32_b32 v226, s49, v226
	v_lshl_add_u32 v226, v226, 2, s36
	s_mov_b64 exec, s[48:49]
	ds_write_b32 v226, v107
	s_mov_b64 exec, s[100:101]
	s_bcnt1_i32_b64 s99, s[48:49]
	s_lshl_b32 s99, s99, 2
	s_add_i32 s36, s36, s99
	v_cmp_gt_u32_e64 s[46:47], v124, s42
	s_nop 1
	v_mbcnt_lo_u32_b32 v226, s46, 0
	v_mbcnt_hi_u32_b32 v226, s47, v226
	v_lshl_add_u32 v226, v226, 2, s36
	s_mov_b64 exec, s[46:47]
	ds_write_b32 v226, v108
	s_mov_b64 exec, s[100:101]
	s_bcnt1_i32_b64 s99, s[46:47]
	s_lshl_b32 s99, s99, 2
	s_add_i32 s36, s36, s99
	v_cmp_gt_u32_e64 s[48:49], v125, s42
	s_nop 1
	v_mbcnt_lo_u32_b32 v226, s48, 0
	v_mbcnt_hi_u32_b32 v226, s49, v226
	v_lshl_add_u32 v226, v226, 2, s36
	s_mov_b64 exec, s[48:49]
	ds_write_b32 v226, v109
	s_mov_b64 exec, s[100:101]
	s_bcnt1_i32_b64 s99, s[48:49]
	s_lshl_b32 s99, s99, 2
	s_add_i32 s36, s36, s99
	v_cmp_gt_u32_e64 s[46:47], v126, s42
	s_nop 1
	v_mbcnt_lo_u32_b32 v226, s46, 0
	v_mbcnt_hi_u32_b32 v226, s47, v226
	v_lshl_add_u32 v226, v226, 2, s36
	s_mov_b64 exec, s[46:47]
	ds_write_b32 v226, v110
	s_mov_b64 exec, s[100:101]
	s_bcnt1_i32_b64 s99, s[46:47]
	s_lshl_b32 s99, s99, 2
	s_add_i32 s36, s36, s99
	v_cmp_gt_u32_e64 s[48:49], v127, s42
	s_nop 1
	v_mbcnt_lo_u32_b32 v226, s48, 0
	v_mbcnt_hi_u32_b32 v226, s49, v226
	v_lshl_add_u32 v226, v226, 2, s36
	s_mov_b64 exec, s[48:49]
	ds_write_b32 v226, v111
	s_mov_b64 exec, s[100:101]
	s_bcnt1_i32_b64 s99, s[48:49]
	s_lshl_b32 s99, s99, 2
	s_add_i32 s36, s36, s99
	v_cmp_eq_u32_e64 s[46:47], v112, s42
	s_nop 1
	v_mbcnt_lo_u32_b32 v226, s46, 0
	v_mbcnt_hi_u32_b32 v226, s47, v226
	v_lshl_add_u32 v226, v226, 2, s36
	v_cmp_gt_i32_e64 s[58:59], s84, v226
	s_bcnt1_i32_b64 s99, s[46:47]
	s_lshl_b32 s99, s99, 2
	s_and_b64 exec, s[46:47], s[58:59]
	ds_write_b32 v226, v96
	s_mov_b64 exec, s[100:101]
	s_add_i32 s36, s36, s99
	v_cmp_eq_u32_e64 s[48:49], v113, s42
	s_nop 1
	v_mbcnt_lo_u32_b32 v226, s48, 0
	v_mbcnt_hi_u32_b32 v226, s49, v226
	v_lshl_add_u32 v226, v226, 2, s36
	v_cmp_gt_i32_e64 s[80:81], s84, v226
	s_bcnt1_i32_b64 s99, s[48:49]
	s_lshl_b32 s99, s99, 2
	s_and_b64 exec, s[48:49], s[80:81]
	ds_write_b32 v226, v97
	s_mov_b64 exec, s[100:101]
	s_add_i32 s36, s36, s99
	v_cmp_eq_u32_e64 s[46:47], v114, s42
	s_nop 1
	v_mbcnt_lo_u32_b32 v226, s46, 0
	v_mbcnt_hi_u32_b32 v226, s47, v226
	v_lshl_add_u32 v226, v226, 2, s36
	v_cmp_gt_i32_e64 s[58:59], s84, v226
	s_bcnt1_i32_b64 s99, s[46:47]
	s_lshl_b32 s99, s99, 2
	s_and_b64 exec, s[46:47], s[58:59]
	ds_write_b32 v226, v98
	s_mov_b64 exec, s[100:101]
	s_add_i32 s36, s36, s99
	v_cmp_eq_u32_e64 s[48:49], v115, s42
	s_nop 1
	v_mbcnt_lo_u32_b32 v226, s48, 0
	v_mbcnt_hi_u32_b32 v226, s49, v226
	v_lshl_add_u32 v226, v226, 2, s36
	v_cmp_gt_i32_e64 s[80:81], s84, v226
	s_bcnt1_i32_b64 s99, s[48:49]
	s_lshl_b32 s99, s99, 2
	s_and_b64 exec, s[48:49], s[80:81]
	ds_write_b32 v226, v99
	s_mov_b64 exec, s[100:101]
	s_add_i32 s36, s36, s99
	v_cmp_eq_u32_e64 s[46:47], v116, s42
	s_nop 1
	v_mbcnt_lo_u32_b32 v226, s46, 0
	v_mbcnt_hi_u32_b32 v226, s47, v226
	v_lshl_add_u32 v226, v226, 2, s36
	v_cmp_gt_i32_e64 s[58:59], s84, v226
	s_bcnt1_i32_b64 s99, s[46:47]
	s_lshl_b32 s99, s99, 2
	s_and_b64 exec, s[46:47], s[58:59]
	ds_write_b32 v226, v100
	s_mov_b64 exec, s[100:101]
	s_add_i32 s36, s36, s99
	v_cmp_eq_u32_e64 s[48:49], v117, s42
	s_nop 1
	v_mbcnt_lo_u32_b32 v226, s48, 0
	v_mbcnt_hi_u32_b32 v226, s49, v226
	v_lshl_add_u32 v226, v226, 2, s36
	v_cmp_gt_i32_e64 s[80:81], s84, v226
	s_bcnt1_i32_b64 s99, s[48:49]
	s_lshl_b32 s99, s99, 2
	s_and_b64 exec, s[48:49], s[80:81]
	ds_write_b32 v226, v101
	s_mov_b64 exec, s[100:101]
	s_add_i32 s36, s36, s99
	v_cmp_eq_u32_e64 s[46:47], v118, s42
	s_nop 1
	v_mbcnt_lo_u32_b32 v226, s46, 0
	v_mbcnt_hi_u32_b32 v226, s47, v226
	v_lshl_add_u32 v226, v226, 2, s36
	v_cmp_gt_i32_e64 s[58:59], s84, v226
	s_bcnt1_i32_b64 s99, s[46:47]
	s_lshl_b32 s99, s99, 2
	s_and_b64 exec, s[46:47], s[58:59]
	ds_write_b32 v226, v102
	s_mov_b64 exec, s[100:101]
	s_add_i32 s36, s36, s99
	v_cmp_eq_u32_e64 s[48:49], v119, s42
	s_nop 1
	v_mbcnt_lo_u32_b32 v226, s48, 0
	v_mbcnt_hi_u32_b32 v226, s49, v226
	v_lshl_add_u32 v226, v226, 2, s36
	v_cmp_gt_i32_e64 s[80:81], s84, v226
	s_bcnt1_i32_b64 s99, s[48:49]
	s_lshl_b32 s99, s99, 2
	s_and_b64 exec, s[48:49], s[80:81]
	ds_write_b32 v226, v103
	s_mov_b64 exec, s[100:101]
	s_add_i32 s36, s36, s99
	v_cmp_eq_u32_e64 s[46:47], v120, s42
	s_nop 1
	v_mbcnt_lo_u32_b32 v226, s46, 0
	v_mbcnt_hi_u32_b32 v226, s47, v226
	v_lshl_add_u32 v226, v226, 2, s36
	v_cmp_gt_i32_e64 s[58:59], s84, v226
	s_bcnt1_i32_b64 s99, s[46:47]
	s_lshl_b32 s99, s99, 2
	s_and_b64 exec, s[46:47], s[58:59]
	ds_write_b32 v226, v104
	s_mov_b64 exec, s[100:101]
	s_add_i32 s36, s36, s99
	v_cmp_eq_u32_e64 s[48:49], v121, s42
	s_nop 1
	v_mbcnt_lo_u32_b32 v226, s48, 0
	v_mbcnt_hi_u32_b32 v226, s49, v226
	v_lshl_add_u32 v226, v226, 2, s36
	v_cmp_gt_i32_e64 s[80:81], s84, v226
	s_bcnt1_i32_b64 s99, s[48:49]
	s_lshl_b32 s99, s99, 2
	s_and_b64 exec, s[48:49], s[80:81]
	ds_write_b32 v226, v105
	s_mov_b64 exec, s[100:101]
	s_add_i32 s36, s36, s99
	v_cmp_eq_u32_e64 s[46:47], v122, s42
	s_nop 1
	v_mbcnt_lo_u32_b32 v226, s46, 0
	v_mbcnt_hi_u32_b32 v226, s47, v226
	v_lshl_add_u32 v226, v226, 2, s36
	v_cmp_gt_i32_e64 s[58:59], s84, v226
	s_bcnt1_i32_b64 s99, s[46:47]
	s_lshl_b32 s99, s99, 2
	s_and_b64 exec, s[46:47], s[58:59]
	ds_write_b32 v226, v106
	s_mov_b64 exec, s[100:101]
	s_add_i32 s36, s36, s99
	v_cmp_eq_u32_e64 s[48:49], v123, s42
	s_nop 1
	v_mbcnt_lo_u32_b32 v226, s48, 0
	v_mbcnt_hi_u32_b32 v226, s49, v226
	v_lshl_add_u32 v226, v226, 2, s36
	v_cmp_gt_i32_e64 s[80:81], s84, v226
	s_bcnt1_i32_b64 s99, s[48:49]
	s_lshl_b32 s99, s99, 2
	s_and_b64 exec, s[48:49], s[80:81]
	ds_write_b32 v226, v107
	s_mov_b64 exec, s[100:101]
	s_add_i32 s36, s36, s99
	v_cmp_eq_u32_e64 s[46:47], v124, s42
	s_nop 1
	v_mbcnt_lo_u32_b32 v226, s46, 0
	v_mbcnt_hi_u32_b32 v226, s47, v226
	v_lshl_add_u32 v226, v226, 2, s36
	v_cmp_gt_i32_e64 s[58:59], s84, v226
	s_bcnt1_i32_b64 s99, s[46:47]
	s_lshl_b32 s99, s99, 2
	s_and_b64 exec, s[46:47], s[58:59]
	ds_write_b32 v226, v108
	s_mov_b64 exec, s[100:101]
	s_add_i32 s36, s36, s99
	v_cmp_eq_u32_e64 s[48:49], v125, s42
	s_nop 1
	v_mbcnt_lo_u32_b32 v226, s48, 0
	v_mbcnt_hi_u32_b32 v226, s49, v226
	v_lshl_add_u32 v226, v226, 2, s36
	v_cmp_gt_i32_e64 s[80:81], s84, v226
	s_bcnt1_i32_b64 s99, s[48:49]
	s_lshl_b32 s99, s99, 2
	s_and_b64 exec, s[48:49], s[80:81]
	ds_write_b32 v226, v109
	s_mov_b64 exec, s[100:101]
	s_add_i32 s36, s36, s99
	v_cmp_eq_u32_e64 s[46:47], v126, s42
	s_nop 1
	v_mbcnt_lo_u32_b32 v226, s46, 0
	v_mbcnt_hi_u32_b32 v226, s47, v226
	v_lshl_add_u32 v226, v226, 2, s36
	v_cmp_gt_i32_e64 s[58:59], s84, v226
	s_bcnt1_i32_b64 s99, s[46:47]
	s_lshl_b32 s99, s99, 2
	s_and_b64 exec, s[46:47], s[58:59]
	ds_write_b32 v226, v110
	s_mov_b64 exec, s[100:101]
	s_add_i32 s36, s36, s99
	v_cmp_eq_u32_e64 s[48:49], v127, s42
	s_nop 1
	v_mbcnt_lo_u32_b32 v226, s48, 0
	v_mbcnt_hi_u32_b32 v226, s49, v226
	v_lshl_add_u32 v226, v226, 2, s36
	v_cmp_gt_i32_e64 s[80:81], s84, v226
	s_bcnt1_i32_b64 s99, s[48:49]
	s_lshl_b32 s99, s99, 2
	s_and_b64 exec, s[48:49], s[80:81]
	ds_write_b32 v226, v111
	s_mov_b64 exec, s[100:101]
	s_add_i32 s36, s36, s99
	s_branch .Lfine_done
.Lfine_done:
	s_mov_b64 exec, s[100:101]

.LBB0_517:
	s_or_b64 exec, exec, s[0:1]
	v_readlane_b32 s0, v250, 36
	v_readlane_b32 s1, v250, 37
	s_and_b64 s[36:37], s[0:1], s[44:45]
	s_and_saveexec_b64 s[0:1], s[36:37]
	s_cbranch_execz .LBB0_407
	s_cmp_lg_u32 s86, -1
	s_cselect_b32 s36, s86, 0
	s_cselect_b32 s37, s5, 0
	v_mov_b32_e32 v0, s36
	v_mov_b32_e32 v1, s37
	s_waitcnt vmcnt(0)
	ds_write_b32 v0, v196
	s_waitcnt lgkmcnt(0)
	s_branch .LBB0_407
.LBB0_799:
	s_add_u32 s0, s18, 0xfca8000
	s_addc_u32 s1, s19, 0
	v_readlane_b32 s4, v250, 30
	s_add_u32 s36, s18, 0x24128000
	v_readlane_b32 s5, v250, 31
	s_addc_u32 s37, s19, 0
	s_lshl_b64 s[38:39], s[4:5], 12
	s_mov_b64 s[40:41], s[18:19]
	v_readlane_b32 s4, v252, 19
	v_readlane_b32 s8, v252, 23
	v_readlane_b32 s9, v252, 24
	s_add_u32 s38, s8, s38
	v_readlane_b32 s10, v252, 25
	v_readlane_b32 s11, v252, 26
	s_addc_u32 s39, s9, s39
	v_readlane_b32 s4, v250, 29
	s_mov_b64 s[10:11], s[40:41]
	s_cmpk_gt_i32 s4, 0x7f
	v_readlane_b32 s5, v252, 20
	v_readlane_b32 s6, v252, 21
	v_readlane_b32 s7, v252, 22
	v_readlane_b32 s12, v252, 27
	v_readlane_b32 s13, v252, 28
	v_readlane_b32 s14, v252, 29
	v_readlane_b32 s15, v252, 30
	v_readlane_b32 s16, v252, 31
	v_readlane_b32 s17, v252, 32
	v_readlane_b32 s18, v252, 33
	v_readlane_b32 s19, v252, 34
	s_cbranch_scc1 .LBB0_806
	s_add_u32 s48, s10, 0xec28000
	v_readlane_b32 s58, v250, 29
	s_addc_u32 s49, s11, 0
	s_lshl_b32 s40, s58, 8
	v_readlane_b32 s4, v250, 32
	s_or_b32 s50, s40, 0xb0
	s_lshl_b32 s51, s4, 8
	s_branch .LBB0_802
